# v12 plus 64-byte alignment of the nine GEMM K-loop heads
# baseline (speedup 1.0000x reference)
; template <class Epi>
; __device__ __forceinline__ void gemm_phase(LAS unsigned char* lds, const Gemm g, const Epi& E) {
;     ...
;     for (;;) {
;         const bool has_next = S.next(ui + 1, nxt);
;         const char* nA = has_next ? (const char*)g.A + (size_t)nxt.pm * tstep : cA; const char* nB = has_next ? (const char*)g.Bt + (size_t)nxt.pn * tstep : cB;
; #pragma unroll 1
;         for (int t = 0; t < nt; t += 2) {
;     ...
;         if (!has_next) break;
; #pragma unroll
;         for (int a = 0; a < 2; ++a)
; #pragma unroll
;             for (int b = 0; b < 2; ++b)
; #pragma unroll
;                 for (int m = 0; m < 4; ++m)
; #pragma unroll
;                     for (int n = 0; n < 2; ++n) acc[a][b][m][n] = (f32x4){0.f, 0.f, 0.f, 0.f};
;         cur = nxt; cA = nA; cB = nB; ++ui;
.LBB0_80:
	v_mov_b32_e32 v125, 0
	s_andn2_b64 vcc, exec, s[44:45]
	v_mov_b32_e32 v124, v125
	v_mov_b32_e32 v123, v125
	v_mov_b32_e32 v122, v125
	v_mov_b32_e32 v129, v125
	v_mov_b32_e32 v128, v125
	v_mov_b32_e32 v127, v125
	v_mov_b32_e32 v126, v125
	v_mov_b32_e32 v113, v125
	v_mov_b32_e32 v112, v125
	v_mov_b32_e32 v111, v125
	v_mov_b32_e32 v110, v125
	v_mov_b32_e32 v109, v125
	v_mov_b32_e32 v108, v125
	v_mov_b32_e32 v107, v125
	v_mov_b32_e32 v106, v125
	v_mov_b32_e32 v97, v125
	v_mov_b32_e32 v96, v125
	v_mov_b32_e32 v95, v125
	v_mov_b32_e32 v94, v125
	v_mov_b32_e32 v93, v125
	v_mov_b32_e32 v92, v125
	v_mov_b32_e32 v91, v125
	v_mov_b32_e32 v90, v125
	v_mov_b32_e32 v81, v125
	v_mov_b32_e32 v80, v125
	v_mov_b32_e32 v79, v125
	v_mov_b32_e32 v78, v125
	v_mov_b32_e32 v77, v125
	v_mov_b32_e32 v76, v125
	v_mov_b32_e32 v75, v125
	v_mov_b32_e32 v74, v125
	v_mov_b32_e32 v121, v125
	v_mov_b32_e32 v120, v125
	v_mov_b32_e32 v119, v125
	v_mov_b32_e32 v118, v125
	v_mov_b32_e32 v117, v125
	v_mov_b32_e32 v116, v125
	v_mov_b32_e32 v115, v125
	v_mov_b32_e32 v114, v125
	v_mov_b32_e32 v105, v125
	v_mov_b32_e32 v104, v125
	v_mov_b32_e32 v103, v125
	v_mov_b32_e32 v102, v125
	v_mov_b32_e32 v101, v125
	v_mov_b32_e32 v100, v125
	v_mov_b32_e32 v99, v125
	v_mov_b32_e32 v98, v125
	v_mov_b32_e32 v89, v125
	v_mov_b32_e32 v88, v125
	v_mov_b32_e32 v87, v125
	v_mov_b32_e32 v86, v125
	v_mov_b32_e32 v85, v125
	v_mov_b32_e32 v84, v125
	v_mov_b32_e32 v83, v125
	v_mov_b32_e32 v82, v125
	v_mov_b32_e32 v73, v125
	v_mov_b32_e32 v72, v125
	v_mov_b32_e32 v71, v125
	v_mov_b32_e32 v70, v125
	v_mov_b32_e32 v69, v125
	v_mov_b32_e32 v68, v125
	v_mov_b32_e32 v67, v125
	v_mov_b32_e32 v66, v125
	v_mov_b32_e32 v65, v125
	v_mov_b32_e32 v64, v125
	v_mov_b32_e32 v63, v125
	v_mov_b32_e32 v62, v125
	v_mov_b32_e32 v61, v125
	v_mov_b32_e32 v60, v125
	v_mov_b32_e32 v59, v125
	v_mov_b32_e32 v58, v125
	v_mov_b32_e32 v49, v125
	v_mov_b32_e32 v48, v125
	v_mov_b32_e32 v47, v125
	v_mov_b32_e32 v46, v125
	v_mov_b32_e32 v45, v125
	v_mov_b32_e32 v44, v125
	v_mov_b32_e32 v43, v125
	v_mov_b32_e32 v42, v125
	v_mov_b32_e32 v33, v125
	v_mov_b32_e32 v32, v125
	v_mov_b32_e32 v31, v125
	v_mov_b32_e32 v30, v125
	v_mov_b32_e32 v29, v125
	v_mov_b32_e32 v28, v125
	v_mov_b32_e32 v27, v125
	v_mov_b32_e32 v26, v125
	v_mov_b32_e32 v17, v125
	v_mov_b32_e32 v16, v125
	v_mov_b32_e32 v15, v125
	v_mov_b32_e32 v14, v125
	v_mov_b32_e32 v11, v125
	v_mov_b32_e32 v10, v125
	v_mov_b32_e32 v9, v125
	v_mov_b32_e32 v8, v125
	v_mov_b32_e32 v57, v125
	v_mov_b32_e32 v56, v125
	v_mov_b32_e32 v55, v125
	v_mov_b32_e32 v54, v125
	v_mov_b32_e32 v53, v125
	v_mov_b32_e32 v52, v125
	v_mov_b32_e32 v51, v125
	v_mov_b32_e32 v50, v125
	v_mov_b32_e32 v41, v125
	v_mov_b32_e32 v40, v125
	v_mov_b32_e32 v39, v125
	v_mov_b32_e32 v38, v125
	v_mov_b32_e32 v37, v125
	v_mov_b32_e32 v36, v125
	v_mov_b32_e32 v35, v125
	v_mov_b32_e32 v34, v125
	v_mov_b32_e32 v25, v125
	v_mov_b32_e32 v24, v125
	v_mov_b32_e32 v23, v125
	v_mov_b32_e32 v22, v125
	v_mov_b32_e32 v21, v125
	v_mov_b32_e32 v20, v125
	v_mov_b32_e32 v19, v125
	v_mov_b32_e32 v18, v125
	v_mov_b32_e32 v7, v125
	v_mov_b32_e32 v6, v125
	v_mov_b32_e32 v5, v125
	v_mov_b32_e32 v4, v125
	v_mov_b32_e32 v3, v125
	v_mov_b32_e32 v2, v125
	v_mov_b32_e32 v1, v125
	v_mov_b32_e32 v0, v125
	s_cbranch_vccnz .LBB0_73
	s_add_u32 s46, s46, 0x80
	s_addc_u32 s47, s47, 0
	s_add_u32 s87, s48, 0x100
	v_mov_b32_e32 v0, 0
	s_addc_u32 s88, s49, 0
	s_mov_b32 s48, 0
	v_mov_b32_e32 v1, v0
	v_mov_b32_e32 v2, v0
	v_mov_b32_e32 v3, v0
	v_mov_b32_e32 v4, v0
	v_mov_b32_e32 v5, v0
	v_mov_b32_e32 v6, v0
	v_mov_b32_e32 v7, v0
	v_mov_b32_e32 v18, v0
	v_mov_b32_e32 v19, v0
	v_mov_b32_e32 v20, v0
	v_mov_b32_e32 v21, v0
	v_mov_b32_e32 v22, v0
	v_mov_b32_e32 v23, v0
	v_mov_b32_e32 v24, v0
	v_mov_b32_e32 v25, v0
	v_mov_b32_e32 v34, v0
	v_mov_b32_e32 v35, v0
	v_mov_b32_e32 v36, v0
	v_mov_b32_e32 v37, v0
	v_mov_b32_e32 v38, v0
	v_mov_b32_e32 v39, v0
	v_mov_b32_e32 v40, v0
	v_mov_b32_e32 v41, v0
	v_mov_b32_e32 v50, v0
	v_mov_b32_e32 v51, v0
	v_mov_b32_e32 v52, v0
	v_mov_b32_e32 v53, v0
	v_mov_b32_e32 v54, v0
	v_mov_b32_e32 v55, v0
	v_mov_b32_e32 v56, v0
	v_mov_b32_e32 v57, v0
	v_mov_b32_e32 v8, v0
	v_mov_b32_e32 v9, v0
	v_mov_b32_e32 v10, v0
	v_mov_b32_e32 v11, v0
	v_mov_b32_e32 v14, v0
	v_mov_b32_e32 v15, v0
	v_mov_b32_e32 v16, v0
	v_mov_b32_e32 v17, v0
	v_mov_b32_e32 v26, v0
	v_mov_b32_e32 v27, v0
	v_mov_b32_e32 v28, v0
	v_mov_b32_e32 v29, v0
	v_mov_b32_e32 v30, v0
	v_mov_b32_e32 v31, v0
	v_mov_b32_e32 v32, v0
	v_mov_b32_e32 v33, v0
	v_mov_b32_e32 v42, v0
	v_mov_b32_e32 v43, v0
	v_mov_b32_e32 v44, v0
	v_mov_b32_e32 v45, v0
	v_mov_b32_e32 v46, v0
	v_mov_b32_e32 v47, v0
	v_mov_b32_e32 v48, v0
	v_mov_b32_e32 v49, v0
	v_mov_b32_e32 v58, v0
	v_mov_b32_e32 v59, v0
	v_mov_b32_e32 v60, v0
	v_mov_b32_e32 v61, v0
	v_mov_b32_e32 v62, v0
	v_mov_b32_e32 v63, v0
	v_mov_b32_e32 v64, v0
	v_mov_b32_e32 v65, v0
	v_mov_b32_e32 v66, v0
	v_mov_b32_e32 v67, v0
	v_mov_b32_e32 v68, v0
	v_mov_b32_e32 v69, v0
	v_mov_b32_e32 v70, v0
	v_mov_b32_e32 v71, v0
	v_mov_b32_e32 v72, v0
	v_mov_b32_e32 v73, v0
	v_mov_b32_e32 v82, v0
	v_mov_b32_e32 v83, v0
	v_mov_b32_e32 v84, v0
	v_mov_b32_e32 v85, v0
	v_mov_b32_e32 v86, v0
	v_mov_b32_e32 v87, v0
	v_mov_b32_e32 v88, v0
	v_mov_b32_e32 v89, v0
	v_mov_b32_e32 v98, v0
	v_mov_b32_e32 v99, v0
	v_mov_b32_e32 v100, v0
	v_mov_b32_e32 v101, v0
	v_mov_b32_e32 v102, v0
	v_mov_b32_e32 v103, v0
	v_mov_b32_e32 v104, v0
	v_mov_b32_e32 v105, v0
	v_mov_b32_e32 v114, v0
	v_mov_b32_e32 v115, v0
	v_mov_b32_e32 v116, v0
	v_mov_b32_e32 v117, v0
	v_mov_b32_e32 v118, v0
	v_mov_b32_e32 v119, v0
	v_mov_b32_e32 v120, v0
	v_mov_b32_e32 v121, v0
	v_mov_b32_e32 v74, v0
	v_mov_b32_e32 v75, v0
	v_mov_b32_e32 v76, v0
	v_mov_b32_e32 v77, v0
	v_mov_b32_e32 v78, v0
	v_mov_b32_e32 v79, v0
	v_mov_b32_e32 v80, v0
	v_mov_b32_e32 v81, v0
	v_mov_b32_e32 v90, v0
	v_mov_b32_e32 v91, v0
	v_mov_b32_e32 v92, v0
	v_mov_b32_e32 v93, v0
	v_mov_b32_e32 v94, v0
	v_mov_b32_e32 v95, v0
	v_mov_b32_e32 v96, v0
	v_mov_b32_e32 v97, v0
	v_mov_b32_e32 v106, v0
	v_mov_b32_e32 v107, v0
	v_mov_b32_e32 v108, v0
	v_mov_b32_e32 v109, v0
	v_mov_b32_e32 v110, v0
	v_mov_b32_e32 v111, v0
	v_mov_b32_e32 v112, v0
	v_mov_b32_e32 v113, v0
	v_mov_b32_e32 v126, v0
	v_mov_b32_e32 v127, v0
	v_mov_b32_e32 v128, v0
	v_mov_b32_e32 v129, v0
	v_mov_b32_e32 v122, v0
	v_mov_b32_e32 v123, v0
	v_mov_b32_e32 v124, v0
	v_mov_b32_e32 v125, v0
	.p2align 6

; template <class Epi>
; __device__ __forceinline__ void gemm_phase(LAS unsigned char* lds, const Gemm g, const Epi& E) {
;     ...
;     for (;;) {
;         const bool has_next = S.next(ui + 1, nxt);
;         const char* nA = has_next ? (const char*)g.A + (size_t)nxt.pm * tstep : cA; const char* nB = has_next ? (const char*)g.Bt + (size_t)nxt.pn * tstep : cB;
; #pragma unroll 1
;         for (int t = 0; t < nt; t += 2) {
;     ...
;         if (!has_next) break;
; #pragma unroll
;         for (int a = 0; a < 2; ++a)
; #pragma unroll
;             for (int b = 0; b < 2; ++b)
; #pragma unroll
;                 for (int m = 0; m < 4; ++m)
; #pragma unroll
;                     for (int n = 0; n < 2; ++n) acc[a][b][m][n] = (f32x4){0.f, 0.f, 0.f, 0.f};
;         cur = nxt; cA = nA; cB = nB; ++ui;
.LBB0_158:
	v_mov_b32_e32 v129, 0
	s_andn2_b64 vcc, exec, s[44:45]
	v_mov_b32_e32 v128, 0
	v_mov_b32_e32 v127, 0
	v_mov_b32_e32 v126, 0
	v_mov_b32_e32 v125, 0
	v_mov_b32_e32 v124, 0
	v_mov_b32_e32 v123, 0
	v_mov_b32_e32 v122, 0
	v_mov_b32_e32 v103, 0
	v_mov_b32_e32 v102, 0
	v_mov_b32_e32 v105, 0
	v_mov_b32_e32 v104, 0
	v_mov_b32_e32 v111, 0
	v_mov_b32_e32 v110, 0
	v_mov_b32_e32 v113, 0
	v_mov_b32_e32 v112, 0
	v_mov_b32_e32 v87, 0
	v_mov_b32_e32 v86, 0
	v_mov_b32_e32 v89, 0
	v_mov_b32_e32 v88, 0
	v_mov_b32_e32 v95, 0
	v_mov_b32_e32 v94, 0
	v_mov_b32_e32 v97, 0
	v_mov_b32_e32 v96, 0
	v_mov_b32_e32 v75, 0
	v_mov_b32_e32 v74, 0
	v_mov_b32_e32 v77, 0
	v_mov_b32_e32 v76, 0
	v_mov_b32_e32 v79, 0
	v_mov_b32_e32 v78, 0
	v_mov_b32_e32 v81, 0
	v_mov_b32_e32 v80, 0
	v_mov_b32_e32 v143, 0
	v_mov_b32_e32 v142, 0
	v_mov_b32_e32 v145, 0
	v_mov_b32_e32 v144, 0
	v_mov_b32_e32 v147, 0
	v_mov_b32_e32 v146, 0
	v_mov_b32_e32 v149, 0
	v_mov_b32_e32 v148, 0
	v_mov_b32_e32 v115, 0
	v_mov_b32_e32 v114, 0
	v_mov_b32_e32 v117, 0
	v_mov_b32_e32 v116, 0
	v_mov_b32_e32 v119, 0
	v_mov_b32_e32 v118, 0
	v_mov_b32_e32 v121, 0
	v_mov_b32_e32 v120, 0
	v_mov_b32_e32 v99, 0
	v_mov_b32_e32 v98, 0
	v_mov_b32_e32 v101, 0
	v_mov_b32_e32 v100, 0
	v_mov_b32_e32 v107, 0
	v_mov_b32_e32 v106, 0
	v_mov_b32_e32 v109, 0
	v_mov_b32_e32 v108, 0
	v_mov_b32_e32 v73, 0
	v_mov_b32_e32 v72, 0
	v_mov_b32_e32 v71, 0
	v_mov_b32_e32 v70, 0
	v_mov_b32_e32 v69, 0
	v_mov_b32_e32 v68, 0
	v_mov_b32_e32 v67, 0
	v_mov_b32_e32 v66, 0
	v_mov_b32_e32 v65, 0
	v_mov_b32_e32 v64, 0
	v_mov_b32_e32 v63, 0
	v_mov_b32_e32 v62, 0
	v_mov_b32_e32 v61, 0
	v_mov_b32_e32 v60, 0
	v_mov_b32_e32 v59, 0
	v_mov_b32_e32 v58, 0
	v_mov_b32_e32 v39, 0
	v_mov_b32_e32 v38, 0
	v_mov_b32_e32 v41, 0
	v_mov_b32_e32 v40, 0
	v_mov_b32_e32 v47, 0
	v_mov_b32_e32 v46, 0
	v_mov_b32_e32 v49, 0
	v_mov_b32_e32 v48, 0
	v_mov_b32_e32 v23, 0
	v_mov_b32_e32 v22, 0
	v_mov_b32_e32 v25, 0
	v_mov_b32_e32 v24, 0
	v_mov_b32_e32 v31, 0
	v_mov_b32_e32 v30, 0
	v_mov_b32_e32 v33, 0
	v_mov_b32_e32 v32, 0
	v_mov_b32_e32 v9, 0
	v_mov_b32_e32 v8, 0
	v_mov_b32_e32 v11, 0
	v_mov_b32_e32 v10, 0
	v_mov_b32_e32 v15, 0
	v_mov_b32_e32 v14, 0
	v_mov_b32_e32 v17, 0
	v_mov_b32_e32 v16, 0
	v_mov_b32_e32 v83, 0
	v_mov_b32_e32 v82, 0
	v_mov_b32_e32 v85, 0
	v_mov_b32_e32 v84, 0
	v_mov_b32_e32 v91, 0
	v_mov_b32_e32 v90, 0
	v_mov_b32_e32 v93, 0
	v_mov_b32_e32 v92, 0
	v_mov_b32_e32 v51, 0
	v_mov_b32_e32 v50, 0
	v_mov_b32_e32 v53, 0
	v_mov_b32_e32 v52, 0
	v_mov_b32_e32 v55, 0
	v_mov_b32_e32 v54, 0
	v_mov_b32_e32 v57, 0
	v_mov_b32_e32 v56, 0
	v_mov_b32_e32 v35, 0
	v_mov_b32_e32 v34, 0
	v_mov_b32_e32 v37, 0
	v_mov_b32_e32 v36, 0
	v_mov_b32_e32 v43, 0
	v_mov_b32_e32 v42, 0
	v_mov_b32_e32 v45, 0
	v_mov_b32_e32 v44, 0
	v_mov_b32_e32 v7, 0
	v_mov_b32_e32 v6, 0
	v_mov_b32_e32 v5, 0
	v_mov_b32_e32 v4, 0
	v_mov_b32_e32 v3, 0
	v_mov_b32_e32 v2, 0
	v_mov_b32_e32 v1, 0
	v_mov_b32_e32 v0, 0
	s_cbranch_vccnz .LBB0_147
	s_add_u32 s46, s46, 0x80
	s_addc_u32 s47, s47, 0
	s_add_u32 s87, s48, 0x100
	v_mov_b32_e32 v0, 0
	s_addc_u32 s88, s49, 0
	s_mov_b32 s48, 0
	v_mov_b32_e32 v1, v0
	v_mov_b32_e32 v2, v0
	v_mov_b32_e32 v3, v0
	v_mov_b32_e32 v4, v0
	v_mov_b32_e32 v5, v0
	v_mov_b32_e32 v6, v0
	v_mov_b32_e32 v7, v0
	v_mov_b32_e32 v8, v0
	v_mov_b32_e32 v9, v0
	v_mov_b32_e32 v10, v0
	v_mov_b32_e32 v11, v0
	v_mov_b32_e32 v14, v0
	v_mov_b32_e32 v15, v0
	v_mov_b32_e32 v16, v0
	v_mov_b32_e32 v17, v0
	v_mov_b32_e32 v22, v0
	v_mov_b32_e32 v23, v0
	v_mov_b32_e32 v24, v0
	v_mov_b32_e32 v25, v0
	v_mov_b32_e32 v30, v0
	v_mov_b32_e32 v31, v0
	v_mov_b32_e32 v32, v0
	v_mov_b32_e32 v33, v0
	v_mov_b32_e32 v38, v0
	v_mov_b32_e32 v39, v0
	v_mov_b32_e32 v40, v0
	v_mov_b32_e32 v41, v0
	v_mov_b32_e32 v46, v0
	v_mov_b32_e32 v47, v0
	v_mov_b32_e32 v48, v0
	v_mov_b32_e32 v49, v0
	v_mov_b32_e32 v18, v0
	v_mov_b32_e32 v19, v0
	v_mov_b32_e32 v20, v0
	v_mov_b32_e32 v21, v0
	v_mov_b32_e32 v26, v0
	v_mov_b32_e32 v27, v0
	v_mov_b32_e32 v28, v0
	v_mov_b32_e32 v29, v0
	v_mov_b32_e32 v34, v0
	v_mov_b32_e32 v35, v0
	v_mov_b32_e32 v36, v0
	v_mov_b32_e32 v37, v0
	v_mov_b32_e32 v42, v0
	v_mov_b32_e32 v43, v0
	v_mov_b32_e32 v44, v0
	v_mov_b32_e32 v45, v0
	v_mov_b32_e32 v50, v0
	v_mov_b32_e32 v51, v0
	v_mov_b32_e32 v52, v0
	v_mov_b32_e32 v53, v0
	v_mov_b32_e32 v54, v0
	v_mov_b32_e32 v55, v0
	v_mov_b32_e32 v56, v0
	v_mov_b32_e32 v57, v0
	v_mov_b32_e32 v58, v0
	v_mov_b32_e32 v59, v0
	v_mov_b32_e32 v60, v0
	v_mov_b32_e32 v61, v0
	v_mov_b32_e32 v62, v0
	v_mov_b32_e32 v63, v0
	v_mov_b32_e32 v64, v0
	v_mov_b32_e32 v65, v0
	v_mov_b32_e32 v66, v0
	v_mov_b32_e32 v67, v0
	v_mov_b32_e32 v68, v0
	v_mov_b32_e32 v69, v0
	v_mov_b32_e32 v70, v0
	v_mov_b32_e32 v71, v0
	v_mov_b32_e32 v72, v0
	v_mov_b32_e32 v73, v0
	v_mov_b32_e32 v74, v0
	v_mov_b32_e32 v75, v0
	v_mov_b32_e32 v76, v0
	v_mov_b32_e32 v77, v0
	v_mov_b32_e32 v78, v0
	v_mov_b32_e32 v79, v0
	v_mov_b32_e32 v80, v0
	v_mov_b32_e32 v81, v0
	v_mov_b32_e32 v86, v0
	v_mov_b32_e32 v87, v0
	v_mov_b32_e32 v88, v0
	v_mov_b32_e32 v89, v0
	v_mov_b32_e32 v94, v0
	v_mov_b32_e32 v95, v0
	v_mov_b32_e32 v96, v0
	v_mov_b32_e32 v97, v0
	v_mov_b32_e32 v102, v0
	v_mov_b32_e32 v103, v0
	v_mov_b32_e32 v104, v0
	v_mov_b32_e32 v105, v0
	v_mov_b32_e32 v110, v0
	v_mov_b32_e32 v111, v0
	v_mov_b32_e32 v112, v0
	v_mov_b32_e32 v113, v0
	v_mov_b32_e32 v82, v0
	v_mov_b32_e32 v83, v0
	v_mov_b32_e32 v84, v0
	v_mov_b32_e32 v85, v0
	v_mov_b32_e32 v90, v0
	v_mov_b32_e32 v91, v0
	v_mov_b32_e32 v92, v0
	v_mov_b32_e32 v93, v0
	v_mov_b32_e32 v98, v0
	v_mov_b32_e32 v99, v0
	v_mov_b32_e32 v100, v0
	v_mov_b32_e32 v101, v0
	v_mov_b32_e32 v106, v0
	v_mov_b32_e32 v107, v0
	v_mov_b32_e32 v108, v0
	v_mov_b32_e32 v109, v0
	v_mov_b32_e32 v114, v0
	v_mov_b32_e32 v115, v0
	v_mov_b32_e32 v116, v0
	v_mov_b32_e32 v117, v0
	v_mov_b32_e32 v118, v0
	v_mov_b32_e32 v119, v0
	v_mov_b32_e32 v120, v0
	v_mov_b32_e32 v121, v0
	v_mov_b32_e32 v122, v0
	v_mov_b32_e32 v123, v0
	v_mov_b32_e32 v124, v0
	v_mov_b32_e32 v125, v0
	v_mov_b32_e32 v126, v0
	v_mov_b32_e32 v127, v0
	v_mov_b32_e32 v128, v0
	v_mov_b32_e32 v129, v0
	.p2align 6

; template <class Epi>
; __device__ __forceinline__ void gemm_phase(LAS unsigned char* lds, const Gemm g, const Epi& E) {
;     ...
;     for (;;) {
;         const bool has_next = S.next(ui + 1, nxt);
;         const char* nA = has_next ? (const char*)g.A + (size_t)nxt.pm * tstep : cA; const char* nB = has_next ? (const char*)g.Bt + (size_t)nxt.pn * tstep : cB;
; #pragma unroll 1
;         for (int t = 0; t < nt; t += 2) {
;     ...
;         if (!has_next) break;
; #pragma unroll
;         for (int a = 0; a < 2; ++a)
; #pragma unroll
;             for (int b = 0; b < 2; ++b)
; #pragma unroll
;                 for (int m = 0; m < 4; ++m)
; #pragma unroll
;                     for (int n = 0; n < 2; ++n) acc[a][b][m][n] = (f32x4){0.f, 0.f, 0.f, 0.f};
;         cur = nxt; cA = nA; cB = nB; ++ui;
.LBB0_349:
	v_mov_b32_e32 v125, 0
	s_andn2_b64 vcc, exec, s[44:45]
	v_mov_b32_e32 v124, v125
	v_mov_b32_e32 v123, v125
	v_mov_b32_e32 v122, v125
	v_mov_b32_e32 v129, v125
	v_mov_b32_e32 v128, v125
	v_mov_b32_e32 v127, v125
	v_mov_b32_e32 v126, v125
	v_mov_b32_e32 v113, v125
	v_mov_b32_e32 v112, v125
	v_mov_b32_e32 v111, v125
	v_mov_b32_e32 v110, v125
	v_mov_b32_e32 v109, v125
	v_mov_b32_e32 v108, v125
	v_mov_b32_e32 v107, v125
	v_mov_b32_e32 v106, v125
	v_mov_b32_e32 v97, v125
	v_mov_b32_e32 v96, v125
	v_mov_b32_e32 v95, v125
	v_mov_b32_e32 v94, v125
	v_mov_b32_e32 v93, v125
	v_mov_b32_e32 v92, v125
	v_mov_b32_e32 v91, v125
	v_mov_b32_e32 v90, v125
	v_mov_b32_e32 v81, v125
	v_mov_b32_e32 v80, v125
	v_mov_b32_e32 v79, v125
	v_mov_b32_e32 v78, v125
	v_mov_b32_e32 v77, v125
	v_mov_b32_e32 v76, v125
	v_mov_b32_e32 v75, v125
	v_mov_b32_e32 v74, v125
	v_mov_b32_e32 v121, v125
	v_mov_b32_e32 v120, v125
	v_mov_b32_e32 v119, v125
	v_mov_b32_e32 v118, v125
	v_mov_b32_e32 v117, v125
	v_mov_b32_e32 v116, v125
	v_mov_b32_e32 v115, v125
	v_mov_b32_e32 v114, v125
	v_mov_b32_e32 v105, v125
	v_mov_b32_e32 v104, v125
	v_mov_b32_e32 v103, v125
	v_mov_b32_e32 v102, v125
	v_mov_b32_e32 v101, v125
	v_mov_b32_e32 v100, v125
	v_mov_b32_e32 v99, v125
	v_mov_b32_e32 v98, v125
	v_mov_b32_e32 v89, v125
	v_mov_b32_e32 v88, v125
	v_mov_b32_e32 v87, v125
	v_mov_b32_e32 v86, v125
	v_mov_b32_e32 v85, v125
	v_mov_b32_e32 v84, v125
	v_mov_b32_e32 v83, v125
	v_mov_b32_e32 v82, v125
	v_mov_b32_e32 v73, v125
	v_mov_b32_e32 v72, v125
	v_mov_b32_e32 v71, v125
	v_mov_b32_e32 v70, v125
	v_mov_b32_e32 v69, v125
	v_mov_b32_e32 v68, v125
	v_mov_b32_e32 v67, v125
	v_mov_b32_e32 v66, v125
	v_mov_b32_e32 v65, v125
	v_mov_b32_e32 v64, v125
	v_mov_b32_e32 v63, v125
	v_mov_b32_e32 v62, v125
	v_mov_b32_e32 v61, v125
	v_mov_b32_e32 v60, v125
	v_mov_b32_e32 v59, v125
	v_mov_b32_e32 v58, v125
	v_mov_b32_e32 v49, v125
	v_mov_b32_e32 v48, v125
	v_mov_b32_e32 v47, v125
	v_mov_b32_e32 v46, v125
	v_mov_b32_e32 v45, v125
	v_mov_b32_e32 v44, v125
	v_mov_b32_e32 v43, v125
	v_mov_b32_e32 v42, v125
	v_mov_b32_e32 v33, v125
	v_mov_b32_e32 v32, v125
	v_mov_b32_e32 v31, v125
	v_mov_b32_e32 v30, v125
	v_mov_b32_e32 v29, v125
	v_mov_b32_e32 v28, v125
	v_mov_b32_e32 v27, v125
	v_mov_b32_e32 v26, v125
	v_mov_b32_e32 v17, v125
	v_mov_b32_e32 v16, v125
	v_mov_b32_e32 v15, v125
	v_mov_b32_e32 v14, v125
	v_mov_b32_e32 v11, v125
	v_mov_b32_e32 v10, v125
	v_mov_b32_e32 v9, v125
	v_mov_b32_e32 v8, v125
	v_mov_b32_e32 v57, v125
	v_mov_b32_e32 v56, v125
	v_mov_b32_e32 v55, v125
	v_mov_b32_e32 v54, v125
	v_mov_b32_e32 v53, v125
	v_mov_b32_e32 v52, v125
	v_mov_b32_e32 v51, v125
	v_mov_b32_e32 v50, v125
	v_mov_b32_e32 v41, v125
	v_mov_b32_e32 v40, v125
	v_mov_b32_e32 v39, v125
	v_mov_b32_e32 v38, v125
	v_mov_b32_e32 v37, v125
	v_mov_b32_e32 v36, v125
	v_mov_b32_e32 v35, v125
	v_mov_b32_e32 v34, v125
	v_mov_b32_e32 v25, v125
	v_mov_b32_e32 v24, v125
	v_mov_b32_e32 v23, v125
	v_mov_b32_e32 v22, v125
	v_mov_b32_e32 v21, v125
	v_mov_b32_e32 v20, v125
	v_mov_b32_e32 v19, v125
	v_mov_b32_e32 v18, v125
	v_mov_b32_e32 v7, v125
	v_mov_b32_e32 v6, v125
	v_mov_b32_e32 v5, v125
	v_mov_b32_e32 v4, v125
	v_mov_b32_e32 v3, v125
	v_mov_b32_e32 v2, v125
	v_mov_b32_e32 v1, v125
	v_mov_b32_e32 v0, v125
	s_cbranch_vccnz .LBB0_342
	s_add_u32 s46, s46, 0x80
	s_addc_u32 s47, s47, 0
	s_add_u32 s84, s48, 0x100
	v_mov_b32_e32 v0, 0
	s_addc_u32 s85, s49, 0
	s_mov_b32 s48, 0
	v_mov_b32_e32 v1, v0
	v_mov_b32_e32 v2, v0
	v_mov_b32_e32 v3, v0
	v_mov_b32_e32 v4, v0
	v_mov_b32_e32 v5, v0
	v_mov_b32_e32 v6, v0
	v_mov_b32_e32 v7, v0
	v_mov_b32_e32 v18, v0
	v_mov_b32_e32 v19, v0
	v_mov_b32_e32 v20, v0
	v_mov_b32_e32 v21, v0
	v_mov_b32_e32 v22, v0
	v_mov_b32_e32 v23, v0
	v_mov_b32_e32 v24, v0
	v_mov_b32_e32 v25, v0
	v_mov_b32_e32 v34, v0
	v_mov_b32_e32 v35, v0
	v_mov_b32_e32 v36, v0
	v_mov_b32_e32 v37, v0
	v_mov_b32_e32 v38, v0
	v_mov_b32_e32 v39, v0
	v_mov_b32_e32 v40, v0
	v_mov_b32_e32 v41, v0
	v_mov_b32_e32 v50, v0
	v_mov_b32_e32 v51, v0
	v_mov_b32_e32 v52, v0
	v_mov_b32_e32 v53, v0
	v_mov_b32_e32 v54, v0
	v_mov_b32_e32 v55, v0
	v_mov_b32_e32 v56, v0
	v_mov_b32_e32 v57, v0
	v_mov_b32_e32 v8, v0
	v_mov_b32_e32 v9, v0
	v_mov_b32_e32 v10, v0
	v_mov_b32_e32 v11, v0
	v_mov_b32_e32 v14, v0
	v_mov_b32_e32 v15, v0
	v_mov_b32_e32 v16, v0
	v_mov_b32_e32 v17, v0
	v_mov_b32_e32 v26, v0
	v_mov_b32_e32 v27, v0
	v_mov_b32_e32 v28, v0
	v_mov_b32_e32 v29, v0
	v_mov_b32_e32 v30, v0
	v_mov_b32_e32 v31, v0
	v_mov_b32_e32 v32, v0
	v_mov_b32_e32 v33, v0
	v_mov_b32_e32 v42, v0
	v_mov_b32_e32 v43, v0
	v_mov_b32_e32 v44, v0
	v_mov_b32_e32 v45, v0
	v_mov_b32_e32 v46, v0
	v_mov_b32_e32 v47, v0
	v_mov_b32_e32 v48, v0
	v_mov_b32_e32 v49, v0
	v_mov_b32_e32 v58, v0
	v_mov_b32_e32 v59, v0
	v_mov_b32_e32 v60, v0
	v_mov_b32_e32 v61, v0
	v_mov_b32_e32 v62, v0
	v_mov_b32_e32 v63, v0
	v_mov_b32_e32 v64, v0
	v_mov_b32_e32 v65, v0
	v_mov_b32_e32 v66, v0
	v_mov_b32_e32 v67, v0
	v_mov_b32_e32 v68, v0
	v_mov_b32_e32 v69, v0
	v_mov_b32_e32 v70, v0
	v_mov_b32_e32 v71, v0
	v_mov_b32_e32 v72, v0
	v_mov_b32_e32 v73, v0
	v_mov_b32_e32 v82, v0
	v_mov_b32_e32 v83, v0
	v_mov_b32_e32 v84, v0
	v_mov_b32_e32 v85, v0
	v_mov_b32_e32 v86, v0
	v_mov_b32_e32 v87, v0
	v_mov_b32_e32 v88, v0
	v_mov_b32_e32 v89, v0
	v_mov_b32_e32 v98, v0
	v_mov_b32_e32 v99, v0
	v_mov_b32_e32 v100, v0
	v_mov_b32_e32 v101, v0
	v_mov_b32_e32 v102, v0
	v_mov_b32_e32 v103, v0
	v_mov_b32_e32 v104, v0
	v_mov_b32_e32 v105, v0
	v_mov_b32_e32 v114, v0
	v_mov_b32_e32 v115, v0
	v_mov_b32_e32 v116, v0
	v_mov_b32_e32 v117, v0
	v_mov_b32_e32 v118, v0
	v_mov_b32_e32 v119, v0
	v_mov_b32_e32 v120, v0
	v_mov_b32_e32 v121, v0
	v_mov_b32_e32 v74, v0
	v_mov_b32_e32 v75, v0
	v_mov_b32_e32 v76, v0
	v_mov_b32_e32 v77, v0
	v_mov_b32_e32 v78, v0
	v_mov_b32_e32 v79, v0
	v_mov_b32_e32 v80, v0
	v_mov_b32_e32 v81, v0
	v_mov_b32_e32 v90, v0
	v_mov_b32_e32 v91, v0
	v_mov_b32_e32 v92, v0
	v_mov_b32_e32 v93, v0
	v_mov_b32_e32 v94, v0
	v_mov_b32_e32 v95, v0
	v_mov_b32_e32 v96, v0
	v_mov_b32_e32 v97, v0
	v_mov_b32_e32 v106, v0
	v_mov_b32_e32 v107, v0
	v_mov_b32_e32 v108, v0
	v_mov_b32_e32 v109, v0
	v_mov_b32_e32 v110, v0
	v_mov_b32_e32 v111, v0
	v_mov_b32_e32 v112, v0
	v_mov_b32_e32 v113, v0
	v_mov_b32_e32 v126, v0
	v_mov_b32_e32 v127, v0
	v_mov_b32_e32 v128, v0
	v_mov_b32_e32 v129, v0
	v_mov_b32_e32 v122, v0
	v_mov_b32_e32 v123, v0
	v_mov_b32_e32 v124, v0
	v_mov_b32_e32 v125, v0
	.p2align 6

; template <class Epi>
; __device__ __forceinline__ void gemm_phase(LAS unsigned char* lds, const Gemm g, const Epi& E) {
;     ...
;     for (;;) {
;         const bool has_next = S.next(ui + 1, nxt);
;         const char* nA = has_next ? (const char*)g.A + (size_t)nxt.pm * tstep : cA; const char* nB = has_next ? (const char*)g.Bt + (size_t)nxt.pn * tstep : cB;
; #pragma unroll 1
;         for (int t = 0; t < nt; t += 2) {
;     ...
;         if (!has_next) break;
; #pragma unroll
;         for (int a = 0; a < 2; ++a)
; #pragma unroll
;             for (int b = 0; b < 2; ++b)
; #pragma unroll
;                 for (int m = 0; m < 4; ++m)
; #pragma unroll
;                     for (int n = 0; n < 2; ++n) acc[a][b][m][n] = (f32x4){0.f, 0.f, 0.f, 0.f};
;         cur = nxt; cA = nA; cB = nB; ++ui;
.LBB0_514:
	v_mov_b32_e32 v145, 0
	s_andn2_b64 vcc, exec, s[48:49]
	v_mov_b32_e32 v144, v145
	v_mov_b32_e32 v143, v145
	v_mov_b32_e32 v142, v145
	v_mov_b32_e32 v141, v145
	v_mov_b32_e32 v140, v145
	v_mov_b32_e32 v139, v145
	v_mov_b32_e32 v138, v145
	v_mov_b32_e32 v129, v145
	v_mov_b32_e32 v128, v145
	v_mov_b32_e32 v127, v145
	v_mov_b32_e32 v126, v145
	v_mov_b32_e32 v125, v145
	v_mov_b32_e32 v124, v145
	v_mov_b32_e32 v123, v145
	v_mov_b32_e32 v122, v145
	v_mov_b32_e32 v113, v145
	v_mov_b32_e32 v112, v145
	v_mov_b32_e32 v111, v145
	v_mov_b32_e32 v110, v145
	v_mov_b32_e32 v109, v145
	v_mov_b32_e32 v108, v145
	v_mov_b32_e32 v107, v145
	v_mov_b32_e32 v106, v145
	v_mov_b32_e32 v97, v145
	v_mov_b32_e32 v96, v145
	v_mov_b32_e32 v95, v145
	v_mov_b32_e32 v94, v145
	v_mov_b32_e32 v93, v145
	v_mov_b32_e32 v92, v145
	v_mov_b32_e32 v91, v145
	v_mov_b32_e32 v90, v145
	v_mov_b32_e32 v137, v145
	v_mov_b32_e32 v136, v145
	v_mov_b32_e32 v135, v145
	v_mov_b32_e32 v134, v145
	v_mov_b32_e32 v133, v145
	v_mov_b32_e32 v132, v145
	v_mov_b32_e32 v131, v145
	v_mov_b32_e32 v130, v145
	v_mov_b32_e32 v121, v145
	v_mov_b32_e32 v120, v145
	v_mov_b32_e32 v119, v145
	v_mov_b32_e32 v118, v145
	v_mov_b32_e32 v117, v145
	v_mov_b32_e32 v116, v145
	v_mov_b32_e32 v115, v145
	v_mov_b32_e32 v114, v145
	v_mov_b32_e32 v105, v145
	v_mov_b32_e32 v104, v145
	v_mov_b32_e32 v103, v145
	v_mov_b32_e32 v102, v145
	v_mov_b32_e32 v101, v145
	v_mov_b32_e32 v100, v145
	v_mov_b32_e32 v99, v145
	v_mov_b32_e32 v98, v145
	v_mov_b32_e32 v89, v145
	v_mov_b32_e32 v88, v145
	v_mov_b32_e32 v87, v145
	v_mov_b32_e32 v86, v145
	v_mov_b32_e32 v85, v145
	v_mov_b32_e32 v84, v145
	v_mov_b32_e32 v83, v145
	v_mov_b32_e32 v82, v145
	v_mov_b32_e32 v81, v145
	v_mov_b32_e32 v80, v145
	v_mov_b32_e32 v79, v145
	v_mov_b32_e32 v78, v145
	v_mov_b32_e32 v77, v145
	v_mov_b32_e32 v76, v145
	v_mov_b32_e32 v75, v145
	v_mov_b32_e32 v74, v145
	s_waitcnt vmcnt(0)
	v_mov_b32_e32 v49, v145
	v_mov_b32_e32 v48, v145
	v_mov_b32_e32 v47, v145
	v_mov_b32_e32 v46, v145
	v_mov_b32_e32 v45, v145
	v_mov_b32_e32 v44, v145
	v_mov_b32_e32 v43, v145
	v_mov_b32_e32 v42, v145
	v_mov_b32_e32 v33, v145
	v_mov_b32_e32 v32, v145
	v_mov_b32_e32 v31, v145
	v_mov_b32_e32 v30, v145
	v_mov_b32_e32 v29, v145
	v_mov_b32_e32 v28, v145
	v_mov_b32_e32 v27, v145
	v_mov_b32_e32 v26, v145
	v_mov_b32_e32 v17, v145
	v_mov_b32_e32 v16, v145
	v_mov_b32_e32 v15, v145
	v_mov_b32_e32 v14, v145
	v_mov_b32_e32 v11, v145
	v_mov_b32_e32 v10, v145
	v_mov_b32_e32 v9, v145
	v_mov_b32_e32 v8, v145
	v_mov_b32_e32 v65, v145
	v_mov_b32_e32 v64, v145
	v_mov_b32_e32 v63, v145
	v_mov_b32_e32 v62, v145
	v_mov_b32_e32 v61, v145
	v_mov_b32_e32 v60, v145
	v_mov_b32_e32 v59, v145
	v_mov_b32_e32 v58, v145
	v_mov_b32_e32 v41, v145
	v_mov_b32_e32 v40, v145
	v_mov_b32_e32 v39, v145
	v_mov_b32_e32 v38, v145
	v_mov_b32_e32 v37, v145
	v_mov_b32_e32 v36, v145
	v_mov_b32_e32 v35, v145
	v_mov_b32_e32 v34, v145
	v_mov_b32_e32 v25, v145
	v_mov_b32_e32 v24, v145
	v_mov_b32_e32 v23, v145
	v_mov_b32_e32 v22, v145
	v_mov_b32_e32 v21, v145
	v_mov_b32_e32 v20, v145
	v_mov_b32_e32 v19, v145
	v_mov_b32_e32 v18, v145
	v_mov_b32_e32 v7, v145
	v_mov_b32_e32 v6, v145
	v_mov_b32_e32 v5, v145
	v_mov_b32_e32 v4, v145
	v_mov_b32_e32 v3, v145
	v_mov_b32_e32 v2, v145
	v_mov_b32_e32 v1, v145
	v_mov_b32_e32 v0, v145
	s_cbranch_vccnz .LBB0_517
	s_add_u32 s38, s52, 0x80
	s_addc_u32 s39, s53, 0
	s_add_u32 s86, s40, 0x100
	v_mov_b32_e32 v0, 0
	s_addc_u32 s87, s41, 0
	s_mov_b32 s40, 0
	v_mov_b32_e32 v1, v0
	v_mov_b32_e32 v2, v0
	v_mov_b32_e32 v3, v0
	v_mov_b32_e32 v4, v0
	v_mov_b32_e32 v5, v0
	v_mov_b32_e32 v6, v0
	v_mov_b32_e32 v7, v0
	v_mov_b32_e32 v18, v0
	v_mov_b32_e32 v19, v0
	v_mov_b32_e32 v20, v0
	v_mov_b32_e32 v21, v0
	v_mov_b32_e32 v22, v0
	v_mov_b32_e32 v23, v0
	v_mov_b32_e32 v24, v0
	v_mov_b32_e32 v25, v0
	v_mov_b32_e32 v34, v0
	v_mov_b32_e32 v35, v0
	v_mov_b32_e32 v36, v0
	v_mov_b32_e32 v37, v0
	v_mov_b32_e32 v38, v0
	v_mov_b32_e32 v39, v0
	v_mov_b32_e32 v40, v0
	v_mov_b32_e32 v41, v0
	v_mov_b32_e32 v58, v0
	v_mov_b32_e32 v59, v0
	v_mov_b32_e32 v60, v0
	v_mov_b32_e32 v61, v0
	v_mov_b32_e32 v62, v0
	v_mov_b32_e32 v63, v0
	v_mov_b32_e32 v64, v0
	v_mov_b32_e32 v65, v0
	v_mov_b32_e32 v8, v0
	v_mov_b32_e32 v9, v0
	v_mov_b32_e32 v10, v0
	v_mov_b32_e32 v11, v0
	v_mov_b32_e32 v14, v0
	v_mov_b32_e32 v15, v0
	v_mov_b32_e32 v16, v0
	v_mov_b32_e32 v17, v0
	v_mov_b32_e32 v26, v0
	v_mov_b32_e32 v27, v0
	v_mov_b32_e32 v28, v0
	v_mov_b32_e32 v29, v0
	v_mov_b32_e32 v30, v0
	v_mov_b32_e32 v31, v0
	v_mov_b32_e32 v32, v0
	v_mov_b32_e32 v33, v0
	v_mov_b32_e32 v42, v0
	v_mov_b32_e32 v43, v0
	v_mov_b32_e32 v44, v0
	v_mov_b32_e32 v45, v0
	v_mov_b32_e32 v46, v0
	v_mov_b32_e32 v47, v0
	v_mov_b32_e32 v48, v0
	v_mov_b32_e32 v49, v0
	v_mov_b32_e32 v74, v0
	v_mov_b32_e32 v75, v0
	v_mov_b32_e32 v76, v0
	v_mov_b32_e32 v77, v0
	v_mov_b32_e32 v78, v0
	v_mov_b32_e32 v79, v0
	v_mov_b32_e32 v80, v0
	v_mov_b32_e32 v81, v0
	v_mov_b32_e32 v82, v0
	v_mov_b32_e32 v83, v0
	v_mov_b32_e32 v84, v0
	v_mov_b32_e32 v85, v0
	v_mov_b32_e32 v86, v0
	v_mov_b32_e32 v87, v0
	v_mov_b32_e32 v88, v0
	v_mov_b32_e32 v89, v0
	v_mov_b32_e32 v98, v0
	v_mov_b32_e32 v99, v0
	v_mov_b32_e32 v100, v0
	v_mov_b32_e32 v101, v0
	v_mov_b32_e32 v102, v0
	v_mov_b32_e32 v103, v0
	v_mov_b32_e32 v104, v0
	v_mov_b32_e32 v105, v0
	v_mov_b32_e32 v114, v0
	v_mov_b32_e32 v115, v0
	v_mov_b32_e32 v116, v0
	v_mov_b32_e32 v117, v0
	v_mov_b32_e32 v118, v0
	v_mov_b32_e32 v119, v0
	v_mov_b32_e32 v120, v0
	v_mov_b32_e32 v121, v0
	v_mov_b32_e32 v130, v0
	v_mov_b32_e32 v131, v0
	v_mov_b32_e32 v132, v0
	v_mov_b32_e32 v133, v0
	v_mov_b32_e32 v134, v0
	v_mov_b32_e32 v135, v0
	v_mov_b32_e32 v136, v0
	v_mov_b32_e32 v137, v0
	v_mov_b32_e32 v90, v0
	v_mov_b32_e32 v91, v0
	v_mov_b32_e32 v92, v0
	v_mov_b32_e32 v93, v0
	v_mov_b32_e32 v94, v0
	v_mov_b32_e32 v95, v0
	v_mov_b32_e32 v96, v0
	v_mov_b32_e32 v97, v0
	v_mov_b32_e32 v106, v0
	v_mov_b32_e32 v107, v0
	v_mov_b32_e32 v108, v0
	v_mov_b32_e32 v109, v0
	v_mov_b32_e32 v110, v0
	v_mov_b32_e32 v111, v0
	v_mov_b32_e32 v112, v0
	v_mov_b32_e32 v113, v0
	v_mov_b32_e32 v122, v0
	v_mov_b32_e32 v123, v0
	v_mov_b32_e32 v124, v0
	v_mov_b32_e32 v125, v0
	v_mov_b32_e32 v126, v0
	v_mov_b32_e32 v127, v0
	v_mov_b32_e32 v128, v0
	v_mov_b32_e32 v129, v0
	v_mov_b32_e32 v138, v0
	v_mov_b32_e32 v139, v0
	v_mov_b32_e32 v140, v0
	v_mov_b32_e32 v141, v0
	v_mov_b32_e32 v142, v0
	v_mov_b32_e32 v143, v0
	v_mov_b32_e32 v144, v0
	v_mov_b32_e32 v145, v0
	.p2align 6

; template <class Epi>
; __device__ __forceinline__ void gemm_phase(LAS unsigned char* lds, const Gemm g, const Epi& E) {
;     ...
;     for (;;) {
;         const bool has_next = S.next(ui + 1, nxt);
;         const char* nA = has_next ? (const char*)g.A + (size_t)nxt.pm * tstep : cA; const char* nB = has_next ? (const char*)g.Bt + (size_t)nxt.pn * tstep : cB;
; #pragma unroll 1
;         for (int t = 0; t < nt; t += 2) {
;     ...
;         if (!has_next) break;
; #pragma unroll
;         for (int a = 0; a < 2; ++a)
; #pragma unroll
;             for (int b = 0; b < 2; ++b)
; #pragma unroll
;                 for (int m = 0; m < 4; ++m)
; #pragma unroll
;                     for (int n = 0; n < 2; ++n) acc[a][b][m][n] = (f32x4){0.f, 0.f, 0.f, 0.f};
;         cur = nxt; cA = nA; cB = nB; ++ui;
.LBB0_668:
	v_mov_b32_e32 v145, 0
	s_andn2_b64 vcc, exec, s[44:45]
	v_mov_b32_e32 v144, v145
	v_mov_b32_e32 v143, v145
	v_mov_b32_e32 v142, v145
	v_mov_b32_e32 v141, v145
	v_mov_b32_e32 v140, v145
	v_mov_b32_e32 v139, v145
	v_mov_b32_e32 v138, v145
	v_mov_b32_e32 v129, v145
	v_mov_b32_e32 v128, v145
	v_mov_b32_e32 v127, v145
	v_mov_b32_e32 v126, v145
	v_mov_b32_e32 v125, v145
	v_mov_b32_e32 v124, v145
	v_mov_b32_e32 v123, v145
	v_mov_b32_e32 v122, v145
	v_mov_b32_e32 v113, v145
	v_mov_b32_e32 v112, v145
	v_mov_b32_e32 v111, v145
	v_mov_b32_e32 v110, v145
	v_mov_b32_e32 v109, v145
	v_mov_b32_e32 v108, v145
	v_mov_b32_e32 v107, v145
	v_mov_b32_e32 v106, v145
	v_mov_b32_e32 v97, v145
	v_mov_b32_e32 v96, v145
	v_mov_b32_e32 v95, v145
	v_mov_b32_e32 v94, v145
	v_mov_b32_e32 v93, v145
	v_mov_b32_e32 v92, v145
	v_mov_b32_e32 v91, v145
	v_mov_b32_e32 v90, v145
	v_mov_b32_e32 v137, v145
	v_mov_b32_e32 v136, v145
	v_mov_b32_e32 v135, v145
	v_mov_b32_e32 v134, v145
	v_mov_b32_e32 v133, v145
	v_mov_b32_e32 v132, v145
	v_mov_b32_e32 v131, v145
	v_mov_b32_e32 v130, v145
	v_mov_b32_e32 v121, v145
	v_mov_b32_e32 v120, v145
	v_mov_b32_e32 v119, v145
	v_mov_b32_e32 v118, v145
	v_mov_b32_e32 v117, v145
	v_mov_b32_e32 v116, v145
	v_mov_b32_e32 v115, v145
	v_mov_b32_e32 v114, v145
	v_mov_b32_e32 v105, v145
	v_mov_b32_e32 v104, v145
	v_mov_b32_e32 v103, v145
	v_mov_b32_e32 v102, v145
	v_mov_b32_e32 v101, v145
	v_mov_b32_e32 v100, v145
	v_mov_b32_e32 v99, v145
	v_mov_b32_e32 v98, v145
	v_mov_b32_e32 v89, v145
	v_mov_b32_e32 v88, v145
	v_mov_b32_e32 v87, v145
	v_mov_b32_e32 v86, v145
	v_mov_b32_e32 v85, v145
	v_mov_b32_e32 v84, v145
	v_mov_b32_e32 v83, v145
	v_mov_b32_e32 v82, v145
	v_mov_b32_e32 v81, v145
	v_mov_b32_e32 v80, v145
	v_mov_b32_e32 v79, v145
	v_mov_b32_e32 v78, v145
	v_mov_b32_e32 v77, v145
	v_mov_b32_e32 v76, v145
	v_mov_b32_e32 v75, v145
	v_mov_b32_e32 v74, v145
	s_waitcnt vmcnt(0)
	v_mov_b32_e32 v61, v145
	v_mov_b32_e32 v60, v145
	v_mov_b32_e32 v59, v145
	v_mov_b32_e32 v58, v145
	v_mov_b32_e32 v53, v145
	v_mov_b32_e32 v52, v145
	v_mov_b32_e32 v51, v145
	v_mov_b32_e32 v50, v145
	v_mov_b32_e32 v33, v145
	v_mov_b32_e32 v32, v145
	v_mov_b32_e32 v31, v145
	v_mov_b32_e32 v30, v145
	v_mov_b32_e32 v29, v145
	v_mov_b32_e32 v28, v145
	v_mov_b32_e32 v27, v145
	v_mov_b32_e32 v26, v145
	v_mov_b32_e32 v17, v145
	v_mov_b32_e32 v16, v145
	v_mov_b32_e32 v15, v145
	v_mov_b32_e32 v14, v145
	v_mov_b32_e32 v11, v145
	v_mov_b32_e32 v10, v145
	v_mov_b32_e32 v9, v145
	v_mov_b32_e32 v8, v145
	v_mov_b32_e32 v73, v145
	v_mov_b32_e32 v72, v145
	v_mov_b32_e32 v71, v145
	v_mov_b32_e32 v70, v145
	v_mov_b32_e32 v69, v145
	v_mov_b32_e32 v68, v145
	v_mov_b32_e32 v67, v145
	v_mov_b32_e32 v66, v145
	v_mov_b32_e32 v45, v145
	v_mov_b32_e32 v44, v145
	v_mov_b32_e32 v43, v145
	v_mov_b32_e32 v42, v145
	v_mov_b32_e32 v37, v145
	v_mov_b32_e32 v36, v145
	v_mov_b32_e32 v35, v145
	v_mov_b32_e32 v34, v145
	v_mov_b32_e32 v25, v145
	v_mov_b32_e32 v24, v145
	v_mov_b32_e32 v23, v145
	v_mov_b32_e32 v22, v145
	v_mov_b32_e32 v21, v145
	v_mov_b32_e32 v20, v145
	v_mov_b32_e32 v19, v145
	v_mov_b32_e32 v18, v145
	v_mov_b32_e32 v7, v145
	v_mov_b32_e32 v6, v145
	v_mov_b32_e32 v5, v145
	v_mov_b32_e32 v4, v145
	v_mov_b32_e32 v3, v145
	v_mov_b32_e32 v2, v145
	v_mov_b32_e32 v1, v145
	v_mov_b32_e32 v0, v145
	s_cbranch_vccnz .LBB0_657
	s_add_u32 s46, s46, 0x80
	s_addc_u32 s47, s47, 0
	s_add_u32 s84, s48, 0x100
	v_mov_b32_e32 v0, 0
	s_addc_u32 s85, s49, 0
	s_mov_b32 s48, 0
	v_mov_b32_e32 v1, v0
	v_mov_b32_e32 v2, v0
	v_mov_b32_e32 v3, v0
	v_mov_b32_e32 v4, v0
	v_mov_b32_e32 v5, v0
	v_mov_b32_e32 v6, v0
	v_mov_b32_e32 v7, v0
	v_mov_b32_e32 v18, v0
	v_mov_b32_e32 v19, v0
	v_mov_b32_e32 v20, v0
	v_mov_b32_e32 v21, v0
	v_mov_b32_e32 v22, v0
	v_mov_b32_e32 v23, v0
	v_mov_b32_e32 v24, v0
	v_mov_b32_e32 v25, v0
	v_mov_b32_e32 v34, v0
	v_mov_b32_e32 v35, v0
	v_mov_b32_e32 v36, v0
	v_mov_b32_e32 v37, v0
	v_mov_b32_e32 v42, v0
	v_mov_b32_e32 v43, v0
	v_mov_b32_e32 v44, v0
	v_mov_b32_e32 v45, v0
	v_mov_b32_e32 v66, v0
	v_mov_b32_e32 v67, v0
	v_mov_b32_e32 v68, v0
	v_mov_b32_e32 v69, v0
	v_mov_b32_e32 v70, v0
	v_mov_b32_e32 v71, v0
	v_mov_b32_e32 v72, v0
	v_mov_b32_e32 v73, v0
	v_mov_b32_e32 v8, v0
	v_mov_b32_e32 v9, v0
	v_mov_b32_e32 v10, v0
	v_mov_b32_e32 v11, v0
	v_mov_b32_e32 v14, v0
	v_mov_b32_e32 v15, v0
	v_mov_b32_e32 v16, v0
	v_mov_b32_e32 v17, v0
	v_mov_b32_e32 v26, v0
	v_mov_b32_e32 v27, v0
	v_mov_b32_e32 v28, v0
	v_mov_b32_e32 v29, v0
	v_mov_b32_e32 v30, v0
	v_mov_b32_e32 v31, v0
	v_mov_b32_e32 v32, v0
	v_mov_b32_e32 v33, v0
	v_mov_b32_e32 v50, v0
	v_mov_b32_e32 v51, v0
	v_mov_b32_e32 v52, v0
	v_mov_b32_e32 v53, v0
	v_mov_b32_e32 v58, v0
	v_mov_b32_e32 v59, v0
	v_mov_b32_e32 v60, v0
	v_mov_b32_e32 v61, v0
	v_mov_b32_e32 v74, v0
	v_mov_b32_e32 v75, v0
	v_mov_b32_e32 v76, v0
	v_mov_b32_e32 v77, v0
	v_mov_b32_e32 v78, v0
	v_mov_b32_e32 v79, v0
	v_mov_b32_e32 v80, v0
	v_mov_b32_e32 v81, v0
	v_mov_b32_e32 v82, v0
	v_mov_b32_e32 v83, v0
	v_mov_b32_e32 v84, v0
	v_mov_b32_e32 v85, v0
	v_mov_b32_e32 v86, v0
	v_mov_b32_e32 v87, v0
	v_mov_b32_e32 v88, v0
	v_mov_b32_e32 v89, v0
	v_mov_b32_e32 v98, v0
	v_mov_b32_e32 v99, v0
	v_mov_b32_e32 v100, v0
	v_mov_b32_e32 v101, v0
	v_mov_b32_e32 v102, v0
	v_mov_b32_e32 v103, v0
	v_mov_b32_e32 v104, v0
	v_mov_b32_e32 v105, v0
	v_mov_b32_e32 v114, v0
	v_mov_b32_e32 v115, v0
	v_mov_b32_e32 v116, v0
	v_mov_b32_e32 v117, v0
	v_mov_b32_e32 v118, v0
	v_mov_b32_e32 v119, v0
	v_mov_b32_e32 v120, v0
	v_mov_b32_e32 v121, v0
	v_mov_b32_e32 v130, v0
	v_mov_b32_e32 v131, v0
	v_mov_b32_e32 v132, v0
	v_mov_b32_e32 v133, v0
	v_mov_b32_e32 v134, v0
	v_mov_b32_e32 v135, v0
	v_mov_b32_e32 v136, v0
	v_mov_b32_e32 v137, v0
	v_mov_b32_e32 v90, v0
	v_mov_b32_e32 v91, v0
	v_mov_b32_e32 v92, v0
	v_mov_b32_e32 v93, v0
	v_mov_b32_e32 v94, v0
	v_mov_b32_e32 v95, v0
	v_mov_b32_e32 v96, v0
	v_mov_b32_e32 v97, v0
	v_mov_b32_e32 v106, v0
	v_mov_b32_e32 v107, v0
	v_mov_b32_e32 v108, v0
	v_mov_b32_e32 v109, v0
	v_mov_b32_e32 v110, v0
	v_mov_b32_e32 v111, v0
	v_mov_b32_e32 v112, v0
	v_mov_b32_e32 v113, v0
	v_mov_b32_e32 v122, v0
	v_mov_b32_e32 v123, v0
	v_mov_b32_e32 v124, v0
	v_mov_b32_e32 v125, v0
	v_mov_b32_e32 v126, v0
	v_mov_b32_e32 v127, v0
	v_mov_b32_e32 v128, v0
	v_mov_b32_e32 v129, v0
	v_mov_b32_e32 v138, v0
	v_mov_b32_e32 v139, v0
	v_mov_b32_e32 v140, v0
	v_mov_b32_e32 v141, v0
	v_mov_b32_e32 v142, v0
	v_mov_b32_e32 v143, v0
	v_mov_b32_e32 v144, v0
	v_mov_b32_e32 v145, v0
	.p2align 6

; template <class Epi>
; __device__ __forceinline__ void gemm_phase(LAS unsigned char* lds, const Gemm g, const Epi& E) {
;     ...
;     for (;;) {
;         const bool has_next = S.next(ui + 1, nxt);
;         const char* nA = has_next ? (const char*)g.A + (size_t)nxt.pm * tstep : cA; const char* nB = has_next ? (const char*)g.Bt + (size_t)nxt.pn * tstep : cB;
; #pragma unroll 1
;         for (int t = 0; t < nt; t += 2) {
;     ...
;         if (!has_next) break;
; #pragma unroll
;         for (int a = 0; a < 2; ++a)
; #pragma unroll
;             for (int b = 0; b < 2; ++b)
; #pragma unroll
;                 for (int m = 0; m < 4; ++m)
; #pragma unroll
;                     for (int n = 0; n < 2; ++n) acc[a][b][m][n] = (f32x4){0.f, 0.f, 0.f, 0.f};
;         cur = nxt; cA = nA; cB = nB; ++ui;
.LBB0_928:
	v_mov_b32_e32 v145, 0
	s_andn2_b64 vcc, exec, s[42:43]
	v_mov_b32_e32 v144, v145
	v_mov_b32_e32 v143, v145
	v_mov_b32_e32 v142, v145
	v_mov_b32_e32 v141, v145
	v_mov_b32_e32 v140, v145
	v_mov_b32_e32 v139, v145
	v_mov_b32_e32 v138, v145
	v_mov_b32_e32 v129, v145
	v_mov_b32_e32 v128, v145
	v_mov_b32_e32 v127, v145
	v_mov_b32_e32 v126, v145
	v_mov_b32_e32 v125, v145
	v_mov_b32_e32 v124, v145
	v_mov_b32_e32 v123, v145
	v_mov_b32_e32 v122, v145
	v_mov_b32_e32 v113, v145
	v_mov_b32_e32 v112, v145
	v_mov_b32_e32 v111, v145
	v_mov_b32_e32 v110, v145
	v_mov_b32_e32 v109, v145
	v_mov_b32_e32 v108, v145
	v_mov_b32_e32 v107, v145
	v_mov_b32_e32 v106, v145
	v_mov_b32_e32 v97, v145
	v_mov_b32_e32 v96, v145
	v_mov_b32_e32 v95, v145
	v_mov_b32_e32 v94, v145
	v_mov_b32_e32 v93, v145
	v_mov_b32_e32 v92, v145
	v_mov_b32_e32 v91, v145
	v_mov_b32_e32 v90, v145
	v_mov_b32_e32 v137, v145
	v_mov_b32_e32 v136, v145
	v_mov_b32_e32 v135, v145
	v_mov_b32_e32 v134, v145
	v_mov_b32_e32 v133, v145
	v_mov_b32_e32 v132, v145
	v_mov_b32_e32 v131, v145
	v_mov_b32_e32 v130, v145
	v_mov_b32_e32 v121, v145
	v_mov_b32_e32 v120, v145
	v_mov_b32_e32 v119, v145
	v_mov_b32_e32 v118, v145
	v_mov_b32_e32 v117, v145
	v_mov_b32_e32 v116, v145
	v_mov_b32_e32 v115, v145
	v_mov_b32_e32 v114, v145
	v_mov_b32_e32 v105, v145
	v_mov_b32_e32 v104, v145
	v_mov_b32_e32 v103, v145
	v_mov_b32_e32 v102, v145
	v_mov_b32_e32 v101, v145
	v_mov_b32_e32 v100, v145
	v_mov_b32_e32 v99, v145
	v_mov_b32_e32 v98, v145
	v_mov_b32_e32 v85, v145
	v_mov_b32_e32 v84, v145
	v_mov_b32_e32 v83, v145
	v_mov_b32_e32 v82, v145
	v_mov_b32_e32 v77, v145
	v_mov_b32_e32 v76, v145
	v_mov_b32_e32 v75, v145
	v_mov_b32_e32 v74, v145
	v_mov_b32_e32 v69, v145
	v_mov_b32_e32 v68, v145
	v_mov_b32_e32 v67, v145
	v_mov_b32_e32 v66, v145
	v_mov_b32_e32 v61, v145
	v_mov_b32_e32 v60, v145
	v_mov_b32_e32 v59, v145
	v_mov_b32_e32 v58, v145
	v_mov_b32_e32 v49, v145
	v_mov_b32_e32 v48, v145
	v_mov_b32_e32 v47, v145
	v_mov_b32_e32 v46, v145
	v_mov_b32_e32 v45, v145
	v_mov_b32_e32 v44, v145
	v_mov_b32_e32 v43, v145
	v_mov_b32_e32 v42, v145
	v_mov_b32_e32 v33, v145
	v_mov_b32_e32 v32, v145
	v_mov_b32_e32 v31, v145
	v_mov_b32_e32 v30, v145
	v_mov_b32_e32 v29, v145
	v_mov_b32_e32 v28, v145
	v_mov_b32_e32 v27, v145
	v_mov_b32_e32 v26, v145
	v_mov_b32_e32 v17, v145
	v_mov_b32_e32 v16, v145
	v_mov_b32_e32 v15, v145
	v_mov_b32_e32 v14, v145
	v_mov_b32_e32 v11, v145
	v_mov_b32_e32 v10, v145
	v_mov_b32_e32 v9, v145
	v_mov_b32_e32 v8, v145
	v_mov_b32_e32 v57, v145
	v_mov_b32_e32 v56, v145
	v_mov_b32_e32 v55, v145
	v_mov_b32_e32 v54, v145
	v_mov_b32_e32 v53, v145
	v_mov_b32_e32 v52, v145
	v_mov_b32_e32 v51, v145
	v_mov_b32_e32 v50, v145
	v_mov_b32_e32 v41, v145
	v_mov_b32_e32 v40, v145
	v_mov_b32_e32 v39, v145
	v_mov_b32_e32 v38, v145
	v_mov_b32_e32 v37, v145
	v_mov_b32_e32 v36, v145
	v_mov_b32_e32 v35, v145
	v_mov_b32_e32 v34, v145
	v_mov_b32_e32 v25, v145
	v_mov_b32_e32 v24, v145
	v_mov_b32_e32 v23, v145
	v_mov_b32_e32 v22, v145
	v_mov_b32_e32 v21, v145
	v_mov_b32_e32 v20, v145
	v_mov_b32_e32 v19, v145
	v_mov_b32_e32 v18, v145
	v_mov_b32_e32 v7, v145
	v_mov_b32_e32 v6, v145
	v_mov_b32_e32 v5, v145
	v_mov_b32_e32 v4, v145
	v_mov_b32_e32 v3, v145
	v_mov_b32_e32 v2, v145
	v_mov_b32_e32 v1, v145
	v_mov_b32_e32 v0, v145
	s_cbranch_vccnz .LBB0_917
	s_add_u32 s44, s44, 0x80
	s_addc_u32 s45, s45, 0
	s_add_u32 s82, s46, 0x100
	v_mov_b32_e32 v0, 0
	s_addc_u32 s83, s47, 0
	s_mov_b32 s46, 0
	v_mov_b32_e32 v1, v0
	v_mov_b32_e32 v2, v0
	v_mov_b32_e32 v3, v0
	v_mov_b32_e32 v4, v0
	v_mov_b32_e32 v5, v0
	v_mov_b32_e32 v6, v0
	v_mov_b32_e32 v7, v0
	v_mov_b32_e32 v18, v0
	v_mov_b32_e32 v19, v0
	v_mov_b32_e32 v20, v0
	v_mov_b32_e32 v21, v0
	v_mov_b32_e32 v22, v0
	v_mov_b32_e32 v23, v0
	v_mov_b32_e32 v24, v0
	v_mov_b32_e32 v25, v0
	v_mov_b32_e32 v34, v0
	v_mov_b32_e32 v35, v0
	v_mov_b32_e32 v36, v0
	v_mov_b32_e32 v37, v0
	v_mov_b32_e32 v38, v0
	v_mov_b32_e32 v39, v0
	v_mov_b32_e32 v40, v0
	v_mov_b32_e32 v41, v0
	v_mov_b32_e32 v50, v0
	v_mov_b32_e32 v51, v0
	v_mov_b32_e32 v52, v0
	v_mov_b32_e32 v53, v0
	v_mov_b32_e32 v54, v0
	v_mov_b32_e32 v55, v0
	v_mov_b32_e32 v56, v0
	v_mov_b32_e32 v57, v0
	v_mov_b32_e32 v8, v0
	v_mov_b32_e32 v9, v0
	v_mov_b32_e32 v10, v0
	v_mov_b32_e32 v11, v0
	v_mov_b32_e32 v14, v0
	v_mov_b32_e32 v15, v0
	v_mov_b32_e32 v16, v0
	v_mov_b32_e32 v17, v0
	v_mov_b32_e32 v26, v0
	v_mov_b32_e32 v27, v0
	v_mov_b32_e32 v28, v0
	v_mov_b32_e32 v29, v0
	v_mov_b32_e32 v30, v0
	v_mov_b32_e32 v31, v0
	v_mov_b32_e32 v32, v0
	v_mov_b32_e32 v33, v0
	v_mov_b32_e32 v42, v0
	v_mov_b32_e32 v43, v0
	v_mov_b32_e32 v44, v0
	v_mov_b32_e32 v45, v0
	v_mov_b32_e32 v46, v0
	v_mov_b32_e32 v47, v0
	v_mov_b32_e32 v48, v0
	v_mov_b32_e32 v49, v0
	v_mov_b32_e32 v58, v0
	v_mov_b32_e32 v59, v0
	v_mov_b32_e32 v60, v0
	v_mov_b32_e32 v61, v0
	v_mov_b32_e32 v66, v0
	v_mov_b32_e32 v67, v0
	v_mov_b32_e32 v68, v0
	v_mov_b32_e32 v69, v0
	v_mov_b32_e32 v74, v0
	v_mov_b32_e32 v75, v0
	v_mov_b32_e32 v76, v0
	v_mov_b32_e32 v77, v0
	v_mov_b32_e32 v82, v0
	v_mov_b32_e32 v83, v0
	v_mov_b32_e32 v84, v0
	v_mov_b32_e32 v85, v0
	v_mov_b32_e32 v98, v0
	v_mov_b32_e32 v99, v0
	v_mov_b32_e32 v100, v0
	v_mov_b32_e32 v101, v0
	v_mov_b32_e32 v102, v0
	v_mov_b32_e32 v103, v0
	v_mov_b32_e32 v104, v0
	v_mov_b32_e32 v105, v0
	v_mov_b32_e32 v114, v0
	v_mov_b32_e32 v115, v0
	v_mov_b32_e32 v116, v0
	v_mov_b32_e32 v117, v0
	v_mov_b32_e32 v118, v0
	v_mov_b32_e32 v119, v0
	v_mov_b32_e32 v120, v0
	v_mov_b32_e32 v121, v0
	v_mov_b32_e32 v130, v0
	v_mov_b32_e32 v131, v0
	v_mov_b32_e32 v132, v0
	v_mov_b32_e32 v133, v0
	v_mov_b32_e32 v134, v0
	v_mov_b32_e32 v135, v0
	v_mov_b32_e32 v136, v0
	v_mov_b32_e32 v137, v0
	v_mov_b32_e32 v90, v0
	v_mov_b32_e32 v91, v0
	v_mov_b32_e32 v92, v0
	v_mov_b32_e32 v93, v0
	v_mov_b32_e32 v94, v0
	v_mov_b32_e32 v95, v0
	v_mov_b32_e32 v96, v0
	v_mov_b32_e32 v97, v0
	v_mov_b32_e32 v106, v0
	v_mov_b32_e32 v107, v0
	v_mov_b32_e32 v108, v0
	v_mov_b32_e32 v109, v0
	v_mov_b32_e32 v110, v0
	v_mov_b32_e32 v111, v0
	v_mov_b32_e32 v112, v0
	v_mov_b32_e32 v113, v0
	v_mov_b32_e32 v122, v0
	v_mov_b32_e32 v123, v0
	v_mov_b32_e32 v124, v0
	v_mov_b32_e32 v125, v0
	v_mov_b32_e32 v126, v0
	v_mov_b32_e32 v127, v0
	v_mov_b32_e32 v128, v0
	v_mov_b32_e32 v129, v0
	v_mov_b32_e32 v138, v0
	v_mov_b32_e32 v139, v0
	v_mov_b32_e32 v140, v0
	v_mov_b32_e32 v141, v0
	v_mov_b32_e32 v142, v0
	v_mov_b32_e32 v143, v0
	v_mov_b32_e32 v144, v0
	v_mov_b32_e32 v145, v0
	.p2align 6

; template <class Epi>
; __device__ __forceinline__ void gemm_phase(LAS unsigned char* lds, const Gemm g, const Epi& E) {
;     ...
;     for (;;) {
;         const bool has_next = S.next(ui + 1, nxt);
;         const char* nA = has_next ? (const char*)g.A + (size_t)nxt.pm * tstep : cA; const char* nB = has_next ? (const char*)g.Bt + (size_t)nxt.pn * tstep : cB;
; #pragma unroll 1
;         for (int t = 0; t < nt; t += 2) {
;     ...
;         if (!has_next) break;
; #pragma unroll
;         for (int a = 0; a < 2; ++a)
; #pragma unroll
;             for (int b = 0; b < 2; ++b)
; #pragma unroll
;                 for (int m = 0; m < 4; ++m)
; #pragma unroll
;                     for (int n = 0; n < 2; ++n) acc[a][b][m][n] = (f32x4){0.f, 0.f, 0.f, 0.f};
;         cur = nxt; cA = nA; cB = nB; ++ui;
.LBB0_1006:
	v_mov_b32_e32 v125, 0
	s_andn2_b64 vcc, exec, s[42:43]
	v_mov_b32_e32 v124, v125
	v_mov_b32_e32 v123, v125
	v_mov_b32_e32 v122, v125
	v_mov_b32_e32 v129, v125
	v_mov_b32_e32 v128, v125
	v_mov_b32_e32 v127, v125
	v_mov_b32_e32 v126, v125
	v_mov_b32_e32 v113, v125
	v_mov_b32_e32 v112, v125
	v_mov_b32_e32 v111, v125
	v_mov_b32_e32 v110, v125
	v_mov_b32_e32 v109, v125
	v_mov_b32_e32 v108, v125
	v_mov_b32_e32 v107, v125
	v_mov_b32_e32 v106, v125
	v_mov_b32_e32 v97, v125
	v_mov_b32_e32 v96, v125
	v_mov_b32_e32 v95, v125
	v_mov_b32_e32 v94, v125
	v_mov_b32_e32 v93, v125
	v_mov_b32_e32 v92, v125
	v_mov_b32_e32 v91, v125
	v_mov_b32_e32 v90, v125
	v_mov_b32_e32 v81, v125
	v_mov_b32_e32 v80, v125
	v_mov_b32_e32 v79, v125
	v_mov_b32_e32 v78, v125
	v_mov_b32_e32 v77, v125
	v_mov_b32_e32 v76, v125
	v_mov_b32_e32 v75, v125
	v_mov_b32_e32 v74, v125
	v_mov_b32_e32 v121, v125
	v_mov_b32_e32 v120, v125
	v_mov_b32_e32 v119, v125
	v_mov_b32_e32 v118, v125
	v_mov_b32_e32 v117, v125
	v_mov_b32_e32 v116, v125
	v_mov_b32_e32 v115, v125
	v_mov_b32_e32 v114, v125
	v_mov_b32_e32 v105, v125
	v_mov_b32_e32 v104, v125
	v_mov_b32_e32 v103, v125
	v_mov_b32_e32 v102, v125
	v_mov_b32_e32 v101, v125
	v_mov_b32_e32 v100, v125
	v_mov_b32_e32 v99, v125
	v_mov_b32_e32 v98, v125
	v_mov_b32_e32 v89, v125
	v_mov_b32_e32 v88, v125
	v_mov_b32_e32 v87, v125
	v_mov_b32_e32 v86, v125
	v_mov_b32_e32 v85, v125
	v_mov_b32_e32 v84, v125
	v_mov_b32_e32 v83, v125
	v_mov_b32_e32 v82, v125
	v_mov_b32_e32 v73, v125
	v_mov_b32_e32 v72, v125
	v_mov_b32_e32 v71, v125
	v_mov_b32_e32 v70, v125
	v_mov_b32_e32 v69, v125
	v_mov_b32_e32 v68, v125
	v_mov_b32_e32 v67, v125
	v_mov_b32_e32 v66, v125
	v_mov_b32_e32 v65, v125
	v_mov_b32_e32 v64, v125
	v_mov_b32_e32 v63, v125
	v_mov_b32_e32 v62, v125
	v_mov_b32_e32 v61, v125
	v_mov_b32_e32 v60, v125
	v_mov_b32_e32 v59, v125
	v_mov_b32_e32 v58, v125
	v_mov_b32_e32 v49, v125
	v_mov_b32_e32 v48, v125
	v_mov_b32_e32 v47, v125
	v_mov_b32_e32 v46, v125
	v_mov_b32_e32 v45, v125
	v_mov_b32_e32 v44, v125
	v_mov_b32_e32 v43, v125
	v_mov_b32_e32 v42, v125
	v_mov_b32_e32 v33, v125
	v_mov_b32_e32 v32, v125
	v_mov_b32_e32 v31, v125
	v_mov_b32_e32 v30, v125
	v_mov_b32_e32 v29, v125
	v_mov_b32_e32 v28, v125
	v_mov_b32_e32 v27, v125
	v_mov_b32_e32 v26, v125
	v_mov_b32_e32 v17, v125
	v_mov_b32_e32 v16, v125
	v_mov_b32_e32 v15, v125
	v_mov_b32_e32 v14, v125
	v_mov_b32_e32 v11, v125
	v_mov_b32_e32 v10, v125
	v_mov_b32_e32 v9, v125
	v_mov_b32_e32 v8, v125
	v_mov_b32_e32 v57, v125
	v_mov_b32_e32 v56, v125
	v_mov_b32_e32 v55, v125
	v_mov_b32_e32 v54, v125
	v_mov_b32_e32 v53, v125
	v_mov_b32_e32 v52, v125
	v_mov_b32_e32 v51, v125
	v_mov_b32_e32 v50, v125
	v_mov_b32_e32 v41, v125
	v_mov_b32_e32 v40, v125
	v_mov_b32_e32 v39, v125
	v_mov_b32_e32 v38, v125
	v_mov_b32_e32 v37, v125
	v_mov_b32_e32 v36, v125
	v_mov_b32_e32 v35, v125
	v_mov_b32_e32 v34, v125
	v_mov_b32_e32 v25, v125
	v_mov_b32_e32 v24, v125
	v_mov_b32_e32 v23, v125
	v_mov_b32_e32 v22, v125
	v_mov_b32_e32 v21, v125
	v_mov_b32_e32 v20, v125
	v_mov_b32_e32 v19, v125
	v_mov_b32_e32 v18, v125
	v_mov_b32_e32 v7, v125
	v_mov_b32_e32 v6, v125
	v_mov_b32_e32 v5, v125
	v_mov_b32_e32 v4, v125
	v_mov_b32_e32 v3, v125
	v_mov_b32_e32 v2, v125
	v_mov_b32_e32 v1, v125
	v_mov_b32_e32 v0, v125
	s_cbranch_vccnz .LBB0_995
	s_add_u32 s44, s44, 0x80
	s_addc_u32 s45, s45, 0
	s_add_u32 s82, s46, 0x100
	v_mov_b32_e32 v0, 0
	s_addc_u32 s83, s47, 0
	s_mov_b32 s46, 0
	v_mov_b32_e32 v1, v0
	v_mov_b32_e32 v2, v0
	v_mov_b32_e32 v3, v0
	v_mov_b32_e32 v4, v0
	v_mov_b32_e32 v5, v0
	v_mov_b32_e32 v6, v0
	v_mov_b32_e32 v7, v0
	v_mov_b32_e32 v18, v0
	v_mov_b32_e32 v19, v0
	v_mov_b32_e32 v20, v0
	v_mov_b32_e32 v21, v0
	v_mov_b32_e32 v22, v0
	v_mov_b32_e32 v23, v0
	v_mov_b32_e32 v24, v0
	v_mov_b32_e32 v25, v0
	v_mov_b32_e32 v34, v0
	v_mov_b32_e32 v35, v0
	v_mov_b32_e32 v36, v0
	v_mov_b32_e32 v37, v0
	v_mov_b32_e32 v38, v0
	v_mov_b32_e32 v39, v0
	v_mov_b32_e32 v40, v0
	v_mov_b32_e32 v41, v0
	v_mov_b32_e32 v50, v0
	v_mov_b32_e32 v51, v0
	v_mov_b32_e32 v52, v0
	v_mov_b32_e32 v53, v0
	v_mov_b32_e32 v54, v0
	v_mov_b32_e32 v55, v0
	v_mov_b32_e32 v56, v0
	v_mov_b32_e32 v57, v0
	v_mov_b32_e32 v8, v0
	v_mov_b32_e32 v9, v0
	v_mov_b32_e32 v10, v0
	v_mov_b32_e32 v11, v0
	v_mov_b32_e32 v14, v0
	v_mov_b32_e32 v15, v0
	v_mov_b32_e32 v16, v0
	v_mov_b32_e32 v17, v0
	v_mov_b32_e32 v26, v0
	v_mov_b32_e32 v27, v0
	v_mov_b32_e32 v28, v0
	v_mov_b32_e32 v29, v0
	v_mov_b32_e32 v30, v0
	v_mov_b32_e32 v31, v0
	v_mov_b32_e32 v32, v0
	v_mov_b32_e32 v33, v0
	v_mov_b32_e32 v42, v0
	v_mov_b32_e32 v43, v0
	v_mov_b32_e32 v44, v0
	v_mov_b32_e32 v45, v0
	v_mov_b32_e32 v46, v0
	v_mov_b32_e32 v47, v0
	v_mov_b32_e32 v48, v0
	v_mov_b32_e32 v49, v0
	v_mov_b32_e32 v58, v0
	v_mov_b32_e32 v59, v0
	v_mov_b32_e32 v60, v0
	v_mov_b32_e32 v61, v0
	v_mov_b32_e32 v62, v0
	v_mov_b32_e32 v63, v0
	v_mov_b32_e32 v64, v0
	v_mov_b32_e32 v65, v0
	v_mov_b32_e32 v66, v0
	v_mov_b32_e32 v67, v0
	v_mov_b32_e32 v68, v0
	v_mov_b32_e32 v69, v0
	v_mov_b32_e32 v70, v0
	v_mov_b32_e32 v71, v0
	v_mov_b32_e32 v72, v0
	v_mov_b32_e32 v73, v0
	v_mov_b32_e32 v82, v0
	v_mov_b32_e32 v83, v0
	v_mov_b32_e32 v84, v0
	v_mov_b32_e32 v85, v0
	v_mov_b32_e32 v86, v0
	v_mov_b32_e32 v87, v0
	v_mov_b32_e32 v88, v0
	v_mov_b32_e32 v89, v0
	v_mov_b32_e32 v98, v0
	v_mov_b32_e32 v99, v0
	v_mov_b32_e32 v100, v0
	v_mov_b32_e32 v101, v0
	v_mov_b32_e32 v102, v0
	v_mov_b32_e32 v103, v0
	v_mov_b32_e32 v104, v0
	v_mov_b32_e32 v105, v0
	v_mov_b32_e32 v114, v0
	v_mov_b32_e32 v115, v0
	v_mov_b32_e32 v116, v0
	v_mov_b32_e32 v117, v0
	v_mov_b32_e32 v118, v0
	v_mov_b32_e32 v119, v0
	v_mov_b32_e32 v120, v0
	v_mov_b32_e32 v121, v0
	v_mov_b32_e32 v74, v0
	v_mov_b32_e32 v75, v0
	v_mov_b32_e32 v76, v0
	v_mov_b32_e32 v77, v0
	v_mov_b32_e32 v78, v0
	v_mov_b32_e32 v79, v0
	v_mov_b32_e32 v80, v0
	v_mov_b32_e32 v81, v0
	v_mov_b32_e32 v90, v0
	v_mov_b32_e32 v91, v0
	v_mov_b32_e32 v92, v0
	v_mov_b32_e32 v93, v0
	v_mov_b32_e32 v94, v0
	v_mov_b32_e32 v95, v0
	v_mov_b32_e32 v96, v0
	v_mov_b32_e32 v97, v0
	v_mov_b32_e32 v106, v0
	v_mov_b32_e32 v107, v0
	v_mov_b32_e32 v108, v0
	v_mov_b32_e32 v109, v0
	v_mov_b32_e32 v110, v0
	v_mov_b32_e32 v111, v0
	v_mov_b32_e32 v112, v0
	v_mov_b32_e32 v113, v0
	v_mov_b32_e32 v126, v0
	v_mov_b32_e32 v127, v0
	v_mov_b32_e32 v128, v0
	v_mov_b32_e32 v129, v0
	v_mov_b32_e32 v122, v0
	v_mov_b32_e32 v123, v0
	v_mov_b32_e32 v124, v0
	v_mov_b32_e32 v125, v0
	.p2align 6
